# grid barrier: non-leader L1 invalidate issued at arrival instead of after release; XCC leader releases before its own invalidate
# speedup vs baseline: 1.0245x; 1.0088x over previous
.LBB0_1191:
	s_or_b64 exec, exec, s[4:5]
	s_waitcnt vmcnt(0)
	v_readfirstlane_b32 s0, v4
	v_sub_u32_e32 v5, 0, v2
	s_nop 0
	v_add_u32_e32 v4, s0, v3
	v_cvt_f32_u32_e32 v3, v2
	v_rcp_iflag_f32_e32 v3, v3
	s_nop 0
	v_mul_f32_e32 v3, 0x4f7ffffe, v3
	v_cvt_u32_f32_e32 v3, v3
	v_mul_lo_u32 v5, v5, v3
	v_mul_hi_u32 v5, v3, v5
	v_add_u32_e32 v3, v3, v5
	v_mul_hi_u32 v3, v4, v3
	v_mul_lo_u32 v5, v3, v2
	v_sub_u32_e32 v5, v4, v5
	v_cmp_ge_u32_e32 vcc, v5, v2
	v_add_u32_e32 v6, 1, v3
	s_nop 0
	v_cndmask_b32_e32 v3, v3, v6, vcc
	v_sub_u32_e32 v6, v5, v2
	v_cndmask_b32_e32 v5, v5, v6, vcc
	v_cmp_ge_u32_e32 vcc, v5, v2
	v_add_u32_e32 v5, 1, v3
	v_add_u32_e32 v6, 1, v4
	v_cndmask_b32_e32 v3, v3, v5, vcc
	v_mad_u64_u32 v[4:5], s[4:5], v2, v3, v[2:3]
	v_cmp_ne_u32_e32 vcc, v6, v4
	s_and_saveexec_b64 s[4:5], vcc
	s_xor_b64 s[4:5], exec, s[4:5]
	s_cbranch_execz .LBB0_1205
	buffer_inv sc1
	v_readlane_b32 s6, v254, 16
	v_readlane_b32 s7, v254, 17
	s_nop 4
	global_load_dword v0, v1, s[6:7] sc1
	s_waitcnt vmcnt(0)
	v_cmp_eq_u32_e32 vcc, v0, v3
	s_and_saveexec_b64 s[6:7], vcc
	s_cbranch_execz .LBB0_1204
	s_mov_b32 s0, 1
	s_mov_b64 s[8:9], 0
	s_branch .LBB0_1195

.LBB0_1204:
	s_or_b64 exec, exec, s[6:7]
	s_waitcnt vmcnt(0) lgkmcnt(0)
	s_waitcnt vmcnt(0)

.LBB0_1222:
	s_or_b64 exec, exec, s[4:5]
	s_mov_b64 s[4:5], exec
	v_mbcnt_lo_u32_b32 v0, s4, 0
	v_mbcnt_hi_u32_b32 v0, s5, v0
	v_cmp_eq_u32_e32 vcc, 0, v0
	s_waitcnt vmcnt(0)
	s_and_saveexec_b64 s[6:7], vcc
	s_cbranch_execnz .LBB0_1223
	buffer_inv sc1
	s_getpc_b64 s[98:99]

.LBB0_1223:
	s_bcnt1_i32_b64 s0, s[4:5]
	v_readlane_b32 s4, v254, 16
	v_mov_b32_e32 v0, s0
	v_readlane_b32 s5, v254, 17
	s_nop 4
	global_atomic_add v1, v0, s[4:5]
	buffer_inv sc1
	s_getpc_b64 s[98:99]
